# hyena st1 epilogue hand-written (loads one iteration ahead, pk-f32)
# speedup vs baseline: 1.1292x; 1.0120x over previous
; HD float2 cmul(float2 a, float2 b){ return make_float2(a.x*b.x - a.y*b.y, a.x*b.y + a.y*b.x); }
; HD float2 cmulc(float2 a, float2 b){ return make_float2(a.x*b.x + a.y*b.y, a.y*b.x - a.x*b.y); }
; HD void inv12_half(const float2* Z, const float2* twA, const float2* twB, int t, float2& x0, float2& x1){
;   float2 w1=cmul(twA[t>>6],twB[t&63]), w2=cmul(w1,w1), w3=cmul(w2,w1);
;   float2 b0=Z[t], b1=cmulc(Z[t+4096],w1), b2=cmulc(Z[t+8192],w2), b3=cmulc(Z[t+12288],w3);
;   float2 s02=make_float2(b0.x+b2.x,b0.y+b2.y), d02=make_float2(b0.x-b2.x,b0.y-b2.y);
;   float2 s13=make_float2(b1.x+b3.x,b1.y+b3.y), d13=make_float2(b1.x-b3.x,b1.y-b3.y);
;   x0=make_float2(s02.x+s13.x,s02.y+s13.y);
;   x1=make_float2(d02.x-d13.y,d02.y+d13.x);
; }
; __device__ __forceinline__ void phase_hyena(KP kp_, int hf){ asm volatile("" : "+s"(kp_)); const Params p=load_params(kp_);
;     ...
;         if (st==1){ int tq=tid; asm volatile("" : "+v"(tq));
;           _Pragma("unroll 4") for (int i=0;i<8;++i){ int tb=tq+512*i; float2 xr[2]; inv12_half(Z,twA,twB,tb,xr[0],xr[1]);
;             _Pragma("unroll") for (int hh=0;hh<2;++hh){ int t=tb+hh*4096;
;               float u0=hconv3(rv,t,wv0,wv1,wv2,bv_), u1=hconv3(rv+8192,t,wv0,wv1,wv2,bv_);
;               float x0=hconv3(r1,t,wa0,wa1,wa2,ba_), x1=hconv3(r1+8192,t,wa0,wa1,wa2,ba_);
;               float2 y=xr[hh]; y.x*=(1.f/16384.f); y.y*=(1.f/16384.f);
;               Zs[t]=make_float2(x0*(y.x+u0*bias0), x1*(y.y+u1*bias0)); } }
.LBB0_1340:
	s_and_b64 vcc, exec, s[12:13]
	s_cbranch_vccz .LBB0_1343
	v_lshlrev_b32_e32 v6, 1, v86
	v_add_u32_e32 v134, 0x0, v6
	v_add_u32_e32 v135, 0x1000, v6
	v_add_u32_e32 v136, 0x2000, v6
	v_add_u32_e32 v137, 0x3000, v6
	v_add_u32_e32 v138, 0x4000, v6
	v_add_u32_e32 v139, 0x5000, v6
	v_add_u32_e32 v140, 0x6000, v6
	v_add_u32_e32 v141, 0x7000, v6
	v_add_u32_e32 v142, 0x1000000, v6
	v_add_u32_e32 v143, 0x1001000, v6
	v_add_u32_e32 v144, 0x1002000, v6
	v_add_u32_e32 v145, 0x1003000, v6
	v_add_u32_e32 v150, 0x1004000, v6
	v_add_u32_e32 v151, 0x1005000, v6
	v_add_u32_e32 v152, 0x1006000, v6
	v_add_u32_e32 v153, 0x1007000, v6
	v_lshlrev_b32_e32 v5, 3, v86
	v_mov_b32_e32 v8, v5
	v_add_u32_e32 v9, 0x10000, v5
	v_lshrrev_b32_e32 v7, 6, v86
	v_lshl_add_u32 v7, v7, 3, s88
	v_and_b32_e32 v6, 63, v86
	v_lshl_add_u32 v6, v6, 3, s91
	ds_read_b64 v[10:11], v6
	s_sub_u32 s12, s96, 0x2000000
	s_subb_u32 s13, s97, 0
	global_load_ushort v228, v134, s[12:13] offset:0
	global_load_ushort v229, v138, s[12:13] offset:0
	global_load_ushort v230, v142, s[12:13] offset:0
	global_load_ushort v231, v150, s[12:13] offset:0
	global_load_ushort v232, v136, s[12:13] offset:0
	global_load_ushort v233, v140, s[12:13] offset:0
	global_load_ushort v234, v144, s[12:13] offset:0
	global_load_ushort v235, v152, s[12:13] offset:0
	ds_read_b64 v[12:13], v7 offset:0
	ds_read_b64 v[14:15], v8 offset:0
	ds_read_b64 v[16:17], v8 offset:32768
	ds_read_b64 v[18:19], v9 offset:0
	ds_read_b64 v[20:21], v9 offset:32768
	global_load_ushort v240, v134, s[12:13] offset:1024
	global_load_ushort v241, v138, s[12:13] offset:1024
	global_load_ushort v242, v142, s[12:13] offset:1024
	global_load_ushort v243, v150, s[12:13] offset:1024
	global_load_ushort v244, v136, s[12:13] offset:1024
	global_load_ushort v245, v140, s[12:13] offset:1024
	global_load_ushort v246, v144, s[12:13] offset:1024
	global_load_ushort v247, v152, s[12:13] offset:1024
	ds_read_b64 v[58:59], v7 offset:64
	ds_read_b64 v[60:61], v8 offset:4096
	ds_read_b64 v[62:63], v8 offset:36864
	ds_read_b64 v[64:65], v9 offset:4096
	ds_read_b64 v[66:67], v9 offset:36864
	s_waitcnt lgkmcnt(5)
	v_pk_mul_f32 v[222:223], v[12:13], v[10:11] op_sel:[1,1] op_sel_hi:[1,0]
	v_pk_fma_f32 v[22:23], v[12:13], v[10:11], v[222:223] op_sel:[0,0,0] op_sel_hi:[0,1,1] neg_lo:[0,0,1]
	v_pk_mul_f32 v[222:223], v[22:23], v[22:23] op_sel:[1,1] op_sel_hi:[1,0]
	v_pk_fma_f32 v[24:25], v[22:23], v[22:23], v[222:223] op_sel:[0,0,0] op_sel_hi:[0,1,1] neg_lo:[0,0,1]
	v_pk_mul_f32 v[222:223], v[24:25], v[22:23] op_sel:[1,1] op_sel_hi:[1,0]
	v_pk_fma_f32 v[26:27], v[24:25], v[22:23], v[222:223] op_sel:[0,0,0] op_sel_hi:[0,1,1] neg_lo:[0,0,1]
	v_pk_mul_f32 v[222:223], v[16:17], v[22:23] op_sel:[1,1] op_sel_hi:[0,1]
	v_pk_fma_f32 v[28:29], v[16:17], v[22:23], v[222:223] op_sel:[0,0,0] op_sel_hi:[1,0,1] neg_hi:[0,0,1]
	v_pk_mul_f32 v[222:223], v[18:19], v[24:25] op_sel:[1,1] op_sel_hi:[0,1]
	v_pk_fma_f32 v[30:31], v[18:19], v[24:25], v[222:223] op_sel:[0,0,0] op_sel_hi:[1,0,1] neg_hi:[0,0,1]
	v_pk_mul_f32 v[222:223], v[20:21], v[26:27] op_sel:[1,1] op_sel_hi:[0,1]
	v_pk_fma_f32 v[68:69], v[20:21], v[26:27], v[222:223] op_sel:[0,0,0] op_sel_hi:[1,0,1] neg_hi:[0,0,1]
	v_pk_add_f32 v[70:71], v[14:15], v[30:31]
	v_pk_add_f32 v[72:73], v[14:15], v[30:31] neg_lo:[0,1] neg_hi:[0,1]
	v_pk_add_f32 v[74:75], v[28:29], v[68:69]
	v_pk_add_f32 v[80:81], v[28:29], v[68:69] neg_lo:[0,1] neg_hi:[0,1]
	v_pk_add_f32 v[82:83], v[70:71], v[74:75]
	v_pk_add_f32 v[84:85], v[72:73], v[80:81] op_sel:[0,1] op_sel_hi:[1,0] neg_lo:[0,1]
	s_waitcnt vmcnt(8)
	v_lshlrev_b32_e32 v224, 16, v228
	v_lshlrev_b32_e32 v225, 16, v229
	v_mov_b32_e32 v226, 0
	v_mov_b32_e32 v227, 0
	v_mov_b32_e32 v110, 0
	v_mov_b32_e32 v111, 0
	v_mov_b32_dpp v226, v224 wave_shr:1 row_mask:0xf bank_mask:0xf
	v_mov_b32_dpp v227, v225 wave_shr:1 row_mask:0xf bank_mask:0xf
	v_mov_b32_dpp v110, v224 wave_shl:1 row_mask:0xf bank_mask:0xf
	v_mov_b32_dpp v111, v225 wave_shl:1 row_mask:0xf bank_mask:0xf
	v_pk_mul_f32 v[112:113], v[34:35], v[224:225]
	v_pk_fma_f32 v[112:113], v[32:33], v[226:227], v[112:113]
	v_pk_fma_f32 v[112:113], v[36:37], v[110:111], v[112:113]
	v_pk_add_f32 v[114:115], v[38:39], v[112:113]
	v_lshlrev_b32_e32 v224, 16, v230
	v_lshlrev_b32_e32 v225, 16, v231
	v_mov_b32_e32 v226, 0
	v_mov_b32_e32 v227, 0
	v_mov_b32_e32 v110, 0
	v_mov_b32_e32 v111, 0
	v_mov_b32_dpp v226, v224 wave_shr:1 row_mask:0xf bank_mask:0xf
	v_mov_b32_dpp v227, v225 wave_shr:1 row_mask:0xf bank_mask:0xf
	v_mov_b32_dpp v110, v224 wave_shl:1 row_mask:0xf bank_mask:0xf
	v_mov_b32_dpp v111, v225 wave_shl:1 row_mask:0xf bank_mask:0xf
	v_pk_mul_f32 v[112:113], v[42:43], v[224:225]
	v_pk_fma_f32 v[112:113], v[40:41], v[226:227], v[112:113]
	v_pk_fma_f32 v[112:113], v[44:45], v[110:111], v[112:113]
	v_pk_add_f32 v[156:157], v[46:47], v[112:113]
	v_lshlrev_b32_e32 v224, 16, v232
	v_lshlrev_b32_e32 v225, 16, v233
	v_mov_b32_e32 v226, 0
	v_mov_b32_e32 v227, 0
	v_mov_b32_e32 v110, 0
	v_mov_b32_e32 v111, 0
	v_mov_b32_dpp v226, v224 wave_shr:1 row_mask:0xf bank_mask:0xf
	v_mov_b32_dpp v227, v225 wave_shr:1 row_mask:0xf bank_mask:0xf
	v_mov_b32_dpp v110, v224 wave_shl:1 row_mask:0xf bank_mask:0xf
	v_mov_b32_dpp v111, v225 wave_shl:1 row_mask:0xf bank_mask:0xf
	v_pk_mul_f32 v[112:113], v[34:35], v[224:225]
	v_pk_fma_f32 v[112:113], v[32:33], v[226:227], v[112:113]
	v_pk_fma_f32 v[112:113], v[36:37], v[110:111], v[112:113]
	v_pk_add_f32 v[116:117], v[38:39], v[112:113]
	v_lshlrev_b32_e32 v224, 16, v234
	v_lshlrev_b32_e32 v225, 16, v235
	v_mov_b32_e32 v226, 0
	v_mov_b32_e32 v227, 0
	v_mov_b32_e32 v110, 0
	v_mov_b32_e32 v111, 0
; __device__ __forceinline__ float bf2f(u16 h){ return __uint_as_float(((unsigned)h)<<16); }
; __device__ __forceinline__ float hconv3(const u16* __restrict__ row, int t, float w0, float w1, float w2, float bias){
;   float m = bf2f(row[t]);
;   int mi=__float_as_int(m);
;   float l=__int_as_float(__builtin_amdgcn_update_dpp(0, mi, 0x138, 0xf, 0xf, false));
;   float r=__int_as_float(__builtin_amdgcn_update_dpp(0, mi, 0x130, 0xf, 0xf, false));
;   return w0*l+w1*m+w2*r+bias;
; }
; __device__ __forceinline__ void phase_hyena(KP kp_, int hf){ asm volatile("" : "+s"(kp_)); const Params p=load_params(kp_);
;     ...
;         if (st==1){ int tq=tid; asm volatile("" : "+v"(tq));
;           _Pragma("unroll 4") for (int i=0;i<8;++i){ int tb=tq+512*i; float2 xr[2]; inv12_half(Z,twA,twB,tb,xr[0],xr[1]);
;             _Pragma("unroll") for (int hh=0;hh<2;++hh){ int t=tb+hh*4096;
;               float u0=hconv3(rv,t,wv0,wv1,wv2,bv_), u1=hconv3(rv+8192,t,wv0,wv1,wv2,bv_);
;               float x0=hconv3(r1,t,wa0,wa1,wa2,ba_), x1=hconv3(r1+8192,t,wa0,wa1,wa2,ba_);
;               float2 y=xr[hh]; y.x*=(1.f/16384.f); y.y*=(1.f/16384.f);
;               Zs[t]=make_float2(x0*(y.x+u0*bias0), x1*(y.y+u1*bias0)); } }
	v_mov_b32_dpp v226, v224 wave_shr:1 row_mask:0xf bank_mask:0xf
	v_mov_b32_dpp v227, v225 wave_shr:1 row_mask:0xf bank_mask:0xf
	v_mov_b32_dpp v110, v224 wave_shl:1 row_mask:0xf bank_mask:0xf
	v_mov_b32_dpp v111, v225 wave_shl:1 row_mask:0xf bank_mask:0xf
	v_pk_mul_f32 v[112:113], v[42:43], v[224:225]
	v_pk_fma_f32 v[112:113], v[40:41], v[226:227], v[112:113]
	v_pk_fma_f32 v[112:113], v[44:45], v[110:111], v[112:113]
	v_pk_add_f32 v[158:159], v[46:47], v[112:113]
	v_pk_mul_f32 v[114:115], v[48:49], v[114:115]
	v_pk_fma_f32 v[82:83], v[82:83], s[66:67], v[114:115] op_sel_hi:[1,0,1]
	v_pk_mul_f32 v[82:83], v[82:83], v[156:157]
	v_add_u32_e32 v6, 0x0, v5
	global_store_dwordx2 v6, v[82:83], s[80:81]
	v_pk_mul_f32 v[116:117], v[48:49], v[116:117]
	v_pk_fma_f32 v[84:85], v[84:85], s[66:67], v[116:117] op_sel_hi:[1,0,1]
	v_pk_mul_f32 v[84:85], v[84:85], v[158:159]
	v_add_u32_e32 v6, 0x8000, v5
	global_store_dwordx2 v6, v[84:85], s[80:81]
	global_load_ushort v228, v134, s[12:13] offset:2048
	global_load_ushort v229, v138, s[12:13] offset:2048
	global_load_ushort v230, v142, s[12:13] offset:2048
	global_load_ushort v231, v150, s[12:13] offset:2048
	global_load_ushort v232, v136, s[12:13] offset:2048
	global_load_ushort v233, v140, s[12:13] offset:2048
	global_load_ushort v234, v144, s[12:13] offset:2048
	global_load_ushort v235, v152, s[12:13] offset:2048
	ds_read_b64 v[12:13], v7 offset:128
	ds_read_b64 v[14:15], v8 offset:8192
	ds_read_b64 v[16:17], v8 offset:40960
	ds_read_b64 v[18:19], v9 offset:8192
	ds_read_b64 v[20:21], v9 offset:40960
	s_waitcnt lgkmcnt(5)
	v_pk_mul_f32 v[222:223], v[58:59], v[10:11] op_sel:[1,1] op_sel_hi:[1,0]
	v_pk_fma_f32 v[22:23], v[58:59], v[10:11], v[222:223] op_sel:[0,0,0] op_sel_hi:[0,1,1] neg_lo:[0,0,1]
	v_pk_mul_f32 v[222:223], v[22:23], v[22:23] op_sel:[1,1] op_sel_hi:[1,0]
	v_pk_fma_f32 v[24:25], v[22:23], v[22:23], v[222:223] op_sel:[0,0,0] op_sel_hi:[0,1,1] neg_lo:[0,0,1]
	v_pk_mul_f32 v[222:223], v[24:25], v[22:23] op_sel:[1,1] op_sel_hi:[1,0]
	v_pk_fma_f32 v[26:27], v[24:25], v[22:23], v[222:223] op_sel:[0,0,0] op_sel_hi:[0,1,1] neg_lo:[0,0,1]
	v_pk_mul_f32 v[222:223], v[62:63], v[22:23] op_sel:[1,1] op_sel_hi:[0,1]
	v_pk_fma_f32 v[28:29], v[62:63], v[22:23], v[222:223] op_sel:[0,0,0] op_sel_hi:[1,0,1] neg_hi:[0,0,1]
	v_pk_mul_f32 v[222:223], v[64:65], v[24:25] op_sel:[1,1] op_sel_hi:[0,1]
	v_pk_fma_f32 v[30:31], v[64:65], v[24:25], v[222:223] op_sel:[0,0,0] op_sel_hi:[1,0,1] neg_hi:[0,0,1]
	v_pk_mul_f32 v[222:223], v[66:67], v[26:27] op_sel:[1,1] op_sel_hi:[0,1]
	v_pk_fma_f32 v[68:69], v[66:67], v[26:27], v[222:223] op_sel:[0,0,0] op_sel_hi:[1,0,1] neg_hi:[0,0,1]
	v_pk_add_f32 v[70:71], v[60:61], v[30:31]
	v_pk_add_f32 v[72:73], v[60:61], v[30:31] neg_lo:[0,1] neg_hi:[0,1]
	v_pk_add_f32 v[74:75], v[28:29], v[68:69]
	v_pk_add_f32 v[80:81], v[28:29], v[68:69] neg_lo:[0,1] neg_hi:[0,1]
	v_pk_add_f32 v[82:83], v[70:71], v[74:75]
	v_pk_add_f32 v[84:85], v[72:73], v[80:81] op_sel:[0,1] op_sel_hi:[1,0] neg_lo:[0,1]
	s_waitcnt vmcnt(10)
	v_lshlrev_b32_e32 v224, 16, v240
	v_lshlrev_b32_e32 v225, 16, v241
	v_mov_b32_e32 v226, 0
	v_mov_b32_e32 v227, 0
	v_mov_b32_e32 v110, 0
	v_mov_b32_e32 v111, 0
	v_mov_b32_dpp v226, v224 wave_shr:1 row_mask:0xf bank_mask:0xf
	v_mov_b32_dpp v227, v225 wave_shr:1 row_mask:0xf bank_mask:0xf
	v_mov_b32_dpp v110, v224 wave_shl:1 row_mask:0xf bank_mask:0xf
	v_mov_b32_dpp v111, v225 wave_shl:1 row_mask:0xf bank_mask:0xf
	v_pk_mul_f32 v[112:113], v[34:35], v[224:225]
	v_pk_fma_f32 v[112:113], v[32:33], v[226:227], v[112:113]
	v_pk_fma_f32 v[112:113], v[36:37], v[110:111], v[112:113]
	v_pk_add_f32 v[114:115], v[38:39], v[112:113]
	v_lshlrev_b32_e32 v224, 16, v242
	v_lshlrev_b32_e32 v225, 16, v243
	v_mov_b32_e32 v226, 0
	v_mov_b32_e32 v227, 0
	v_mov_b32_e32 v110, 0
	v_mov_b32_e32 v111, 0
	v_mov_b32_dpp v226, v224 wave_shr:1 row_mask:0xf bank_mask:0xf
	v_mov_b32_dpp v227, v225 wave_shr:1 row_mask:0xf bank_mask:0xf
	v_mov_b32_dpp v110, v224 wave_shl:1 row_mask:0xf bank_mask:0xf
	v_mov_b32_dpp v111, v225 wave_shl:1 row_mask:0xf bank_mask:0xf
	v_pk_mul_f32 v[112:113], v[42:43], v[224:225]
	v_pk_fma_f32 v[112:113], v[40:41], v[226:227], v[112:113]
	v_pk_fma_f32 v[112:113], v[44:45], v[110:111], v[112:113]
	v_pk_add_f32 v[156:157], v[46:47], v[112:113]
	v_lshlrev_b32_e32 v224, 16, v244
	v_lshlrev_b32_e32 v225, 16, v245
	v_mov_b32_e32 v226, 0
	v_mov_b32_e32 v227, 0
	v_mov_b32_e32 v110, 0
	v_mov_b32_e32 v111, 0
	v_mov_b32_dpp v226, v224 wave_shr:1 row_mask:0xf bank_mask:0xf
	v_mov_b32_dpp v227, v225 wave_shr:1 row_mask:0xf bank_mask:0xf
	v_mov_b32_dpp v110, v224 wave_shl:1 row_mask:0xf bank_mask:0xf
	v_mov_b32_dpp v111, v225 wave_shl:1 row_mask:0xf bank_mask:0xf
	v_pk_mul_f32 v[112:113], v[34:35], v[224:225]
	v_pk_fma_f32 v[112:113], v[32:33], v[226:227], v[112:113]
	v_pk_fma_f32 v[112:113], v[36:37], v[110:111], v[112:113]
	v_pk_add_f32 v[116:117], v[38:39], v[112:113]
	v_lshlrev_b32_e32 v224, 16, v246
	v_lshlrev_b32_e32 v225, 16, v247
	v_mov_b32_e32 v226, 0
	v_mov_b32_e32 v227, 0
	v_mov_b32_e32 v110, 0
	v_mov_b32_e32 v111, 0
	v_mov_b32_dpp v226, v224 wave_shr:1 row_mask:0xf bank_mask:0xf
	v_mov_b32_dpp v227, v225 wave_shr:1 row_mask:0xf bank_mask:0xf
	v_mov_b32_dpp v110, v224 wave_shl:1 row_mask:0xf bank_mask:0xf
	v_mov_b32_dpp v111, v225 wave_shl:1 row_mask:0xf bank_mask:0xf
	v_pk_mul_f32 v[112:113], v[42:43], v[224:225]
	v_pk_fma_f32 v[112:113], v[40:41], v[226:227], v[112:113]
	v_pk_fma_f32 v[112:113], v[44:45], v[110:111], v[112:113]
	v_pk_add_f32 v[158:159], v[46:47], v[112:113]
	v_pk_mul_f32 v[114:115], v[48:49], v[114:115]
	v_pk_fma_f32 v[82:83], v[82:83], s[66:67], v[114:115] op_sel_hi:[1,0,1]
	v_pk_mul_f32 v[82:83], v[82:83], v[156:157]
	v_add_u32_e32 v6, 0x1000, v5
	global_store_dwordx2 v6, v[82:83], s[80:81]
	v_pk_mul_f32 v[116:117], v[48:49], v[116:117]
	v_pk_fma_f32 v[84:85], v[84:85], s[66:67], v[116:117] op_sel_hi:[1,0,1]
	v_pk_mul_f32 v[84:85], v[84:85], v[158:159]
	v_add_u32_e32 v6, 0x9000, v5
	global_store_dwordx2 v6, v[84:85], s[80:81]
	global_load_ushort v240, v134, s[12:13] offset:3072
	global_load_ushort v241, v138, s[12:13] offset:3072
	global_load_ushort v242, v142, s[12:13] offset:3072
	global_load_ushort v243, v150, s[12:13] offset:3072
	global_load_ushort v244, v136, s[12:13] offset:3072
	global_load_ushort v245, v140, s[12:13] offset:3072
	global_load_ushort v246, v144, s[12:13] offset:3072
	global_load_ushort v247, v152, s[12:13] offset:3072
	ds_read_b64 v[58:59], v7 offset:192
	ds_read_b64 v[60:61], v8 offset:12288
	ds_read_b64 v[62:63], v8 offset:45056
	ds_read_b64 v[64:65], v9 offset:12288
	ds_read_b64 v[66:67], v9 offset:45056
	s_waitcnt lgkmcnt(5)
; HD float2 cmul(float2 a, float2 b){ return make_float2(a.x*b.x - a.y*b.y, a.x*b.y + a.y*b.x); }
; HD float2 cmulc(float2 a, float2 b){ return make_float2(a.x*b.x + a.y*b.y, a.y*b.x - a.x*b.y); }
; HD void inv12_half(const float2* Z, const float2* twA, const float2* twB, int t, float2& x0, float2& x1){
;   float2 w1=cmul(twA[t>>6],twB[t&63]), w2=cmul(w1,w1), w3=cmul(w2,w1);
;   float2 b0=Z[t], b1=cmulc(Z[t+4096],w1), b2=cmulc(Z[t+8192],w2), b3=cmulc(Z[t+12288],w3);
;   float2 s02=make_float2(b0.x+b2.x,b0.y+b2.y), d02=make_float2(b0.x-b2.x,b0.y-b2.y);
;   float2 s13=make_float2(b1.x+b3.x,b1.y+b3.y), d13=make_float2(b1.x-b3.x,b1.y-b3.y);
;   x0=make_float2(s02.x+s13.x,s02.y+s13.y);
;   x1=make_float2(d02.x-d13.y,d02.y+d13.x);
; }
; __device__ __forceinline__ void phase_hyena(KP kp_, int hf){ asm volatile("" : "+s"(kp_)); const Params p=load_params(kp_);
;     ...
;         if (st==1){ int tq=tid; asm volatile("" : "+v"(tq));
;           _Pragma("unroll 4") for (int i=0;i<8;++i){ int tb=tq+512*i; float2 xr[2]; inv12_half(Z,twA,twB,tb,xr[0],xr[1]);
;             _Pragma("unroll") for (int hh=0;hh<2;++hh){ int t=tb+hh*4096;
;               float u0=hconv3(rv,t,wv0,wv1,wv2,bv_), u1=hconv3(rv+8192,t,wv0,wv1,wv2,bv_);
;               float x0=hconv3(r1,t,wa0,wa1,wa2,ba_), x1=hconv3(r1+8192,t,wa0,wa1,wa2,ba_);
;               float2 y=xr[hh]; y.x*=(1.f/16384.f); y.y*=(1.f/16384.f);
;               Zs[t]=make_float2(x0*(y.x+u0*bias0), x1*(y.y+u1*bias0)); } }
	v_pk_mul_f32 v[222:223], v[12:13], v[10:11] op_sel:[1,1] op_sel_hi:[1,0]
	v_pk_fma_f32 v[22:23], v[12:13], v[10:11], v[222:223] op_sel:[0,0,0] op_sel_hi:[0,1,1] neg_lo:[0,0,1]
	v_pk_mul_f32 v[222:223], v[22:23], v[22:23] op_sel:[1,1] op_sel_hi:[1,0]
	v_pk_fma_f32 v[24:25], v[22:23], v[22:23], v[222:223] op_sel:[0,0,0] op_sel_hi:[0,1,1] neg_lo:[0,0,1]
	v_pk_mul_f32 v[222:223], v[24:25], v[22:23] op_sel:[1,1] op_sel_hi:[1,0]
	v_pk_fma_f32 v[26:27], v[24:25], v[22:23], v[222:223] op_sel:[0,0,0] op_sel_hi:[0,1,1] neg_lo:[0,0,1]
	v_pk_mul_f32 v[222:223], v[16:17], v[22:23] op_sel:[1,1] op_sel_hi:[0,1]
	v_pk_fma_f32 v[28:29], v[16:17], v[22:23], v[222:223] op_sel:[0,0,0] op_sel_hi:[1,0,1] neg_hi:[0,0,1]
	v_pk_mul_f32 v[222:223], v[18:19], v[24:25] op_sel:[1,1] op_sel_hi:[0,1]
	v_pk_fma_f32 v[30:31], v[18:19], v[24:25], v[222:223] op_sel:[0,0,0] op_sel_hi:[1,0,1] neg_hi:[0,0,1]
	v_pk_mul_f32 v[222:223], v[20:21], v[26:27] op_sel:[1,1] op_sel_hi:[0,1]
	v_pk_fma_f32 v[68:69], v[20:21], v[26:27], v[222:223] op_sel:[0,0,0] op_sel_hi:[1,0,1] neg_hi:[0,0,1]
	v_pk_add_f32 v[70:71], v[14:15], v[30:31]
	v_pk_add_f32 v[72:73], v[14:15], v[30:31] neg_lo:[0,1] neg_hi:[0,1]
	v_pk_add_f32 v[74:75], v[28:29], v[68:69]
	v_pk_add_f32 v[80:81], v[28:29], v[68:69] neg_lo:[0,1] neg_hi:[0,1]
	v_pk_add_f32 v[82:83], v[70:71], v[74:75]
	v_pk_add_f32 v[84:85], v[72:73], v[80:81] op_sel:[0,1] op_sel_hi:[1,0] neg_lo:[0,1]
	s_waitcnt vmcnt(10)
	v_lshlrev_b32_e32 v224, 16, v228
	v_lshlrev_b32_e32 v225, 16, v229
	v_mov_b32_e32 v226, 0
	v_mov_b32_e32 v227, 0
	v_mov_b32_e32 v110, 0
	v_mov_b32_e32 v111, 0
	v_mov_b32_dpp v226, v224 wave_shr:1 row_mask:0xf bank_mask:0xf
	v_mov_b32_dpp v227, v225 wave_shr:1 row_mask:0xf bank_mask:0xf
	v_mov_b32_dpp v110, v224 wave_shl:1 row_mask:0xf bank_mask:0xf
	v_mov_b32_dpp v111, v225 wave_shl:1 row_mask:0xf bank_mask:0xf
	v_pk_mul_f32 v[112:113], v[34:35], v[224:225]
	v_pk_fma_f32 v[112:113], v[32:33], v[226:227], v[112:113]
	v_pk_fma_f32 v[112:113], v[36:37], v[110:111], v[112:113]
	v_pk_add_f32 v[114:115], v[38:39], v[112:113]
	v_lshlrev_b32_e32 v224, 16, v230
	v_lshlrev_b32_e32 v225, 16, v231
	v_mov_b32_e32 v226, 0
	v_mov_b32_e32 v227, 0
	v_mov_b32_e32 v110, 0
	v_mov_b32_e32 v111, 0
	v_mov_b32_dpp v226, v224 wave_shr:1 row_mask:0xf bank_mask:0xf
	v_mov_b32_dpp v227, v225 wave_shr:1 row_mask:0xf bank_mask:0xf
	v_mov_b32_dpp v110, v224 wave_shl:1 row_mask:0xf bank_mask:0xf
	v_mov_b32_dpp v111, v225 wave_shl:1 row_mask:0xf bank_mask:0xf
	v_pk_mul_f32 v[112:113], v[42:43], v[224:225]
	v_pk_fma_f32 v[112:113], v[40:41], v[226:227], v[112:113]
	v_pk_fma_f32 v[112:113], v[44:45], v[110:111], v[112:113]
	v_pk_add_f32 v[156:157], v[46:47], v[112:113]
	v_lshlrev_b32_e32 v224, 16, v232
	v_lshlrev_b32_e32 v225, 16, v233
	v_mov_b32_e32 v226, 0
	v_mov_b32_e32 v227, 0
	v_mov_b32_e32 v110, 0
	v_mov_b32_e32 v111, 0
	v_mov_b32_dpp v226, v224 wave_shr:1 row_mask:0xf bank_mask:0xf
	v_mov_b32_dpp v227, v225 wave_shr:1 row_mask:0xf bank_mask:0xf
	v_mov_b32_dpp v110, v224 wave_shl:1 row_mask:0xf bank_mask:0xf
	v_mov_b32_dpp v111, v225 wave_shl:1 row_mask:0xf bank_mask:0xf
	v_pk_mul_f32 v[112:113], v[34:35], v[224:225]
	v_pk_fma_f32 v[112:113], v[32:33], v[226:227], v[112:113]
	v_pk_fma_f32 v[112:113], v[36:37], v[110:111], v[112:113]
	v_pk_add_f32 v[116:117], v[38:39], v[112:113]
	v_lshlrev_b32_e32 v224, 16, v234
	v_lshlrev_b32_e32 v225, 16, v235
	v_mov_b32_e32 v226, 0
	v_mov_b32_e32 v227, 0
	v_mov_b32_e32 v110, 0
	v_mov_b32_e32 v111, 0
	v_mov_b32_dpp v226, v224 wave_shr:1 row_mask:0xf bank_mask:0xf
	v_mov_b32_dpp v227, v225 wave_shr:1 row_mask:0xf bank_mask:0xf
	v_mov_b32_dpp v110, v224 wave_shl:1 row_mask:0xf bank_mask:0xf
	v_mov_b32_dpp v111, v225 wave_shl:1 row_mask:0xf bank_mask:0xf
	v_pk_mul_f32 v[112:113], v[42:43], v[224:225]
	v_pk_fma_f32 v[112:113], v[40:41], v[226:227], v[112:113]
	v_pk_fma_f32 v[112:113], v[44:45], v[110:111], v[112:113]
	v_pk_add_f32 v[158:159], v[46:47], v[112:113]
	v_pk_mul_f32 v[114:115], v[48:49], v[114:115]
	v_pk_fma_f32 v[82:83], v[82:83], s[66:67], v[114:115] op_sel_hi:[1,0,1]
	v_pk_mul_f32 v[82:83], v[82:83], v[156:157]
	v_add_u32_e32 v6, 0x2000, v5
	global_store_dwordx2 v6, v[82:83], s[80:81]
	v_pk_mul_f32 v[116:117], v[48:49], v[116:117]
	v_pk_fma_f32 v[84:85], v[84:85], s[66:67], v[116:117] op_sel_hi:[1,0,1]
	v_pk_mul_f32 v[84:85], v[84:85], v[158:159]
	v_add_u32_e32 v6, 0xa000, v5
	global_store_dwordx2 v6, v[84:85], s[80:81]
	global_load_ushort v228, v135, s[12:13] offset:0
	global_load_ushort v229, v139, s[12:13] offset:0
	global_load_ushort v230, v143, s[12:13] offset:0
	global_load_ushort v231, v151, s[12:13] offset:0
	global_load_ushort v232, v137, s[12:13] offset:0
	global_load_ushort v233, v141, s[12:13] offset:0
	global_load_ushort v234, v145, s[12:13] offset:0
	global_load_ushort v235, v153, s[12:13] offset:0
	ds_read_b64 v[12:13], v7 offset:256
	ds_read_b64 v[14:15], v8 offset:16384
	ds_read_b64 v[16:17], v8 offset:49152
	ds_read_b64 v[18:19], v9 offset:16384
	ds_read_b64 v[20:21], v9 offset:49152
	s_waitcnt lgkmcnt(5)
; HD float2 cmul(float2 a, float2 b){ return make_float2(a.x*b.x - a.y*b.y, a.x*b.y + a.y*b.x); }
; HD float2 cmulc(float2 a, float2 b){ return make_float2(a.x*b.x + a.y*b.y, a.y*b.x - a.x*b.y); }
; HD void inv12_half(const float2* Z, const float2* twA, const float2* twB, int t, float2& x0, float2& x1){
;   float2 w1=cmul(twA[t>>6],twB[t&63]), w2=cmul(w1,w1), w3=cmul(w2,w1);
;   float2 b0=Z[t], b1=cmulc(Z[t+4096],w1), b2=cmulc(Z[t+8192],w2), b3=cmulc(Z[t+12288],w3);
;   float2 s02=make_float2(b0.x+b2.x,b0.y+b2.y), d02=make_float2(b0.x-b2.x,b0.y-b2.y);
;   float2 s13=make_float2(b1.x+b3.x,b1.y+b3.y), d13=make_float2(b1.x-b3.x,b1.y-b3.y);
;   x0=make_float2(s02.x+s13.x,s02.y+s13.y);
;   x1=make_float2(d02.x-d13.y,d02.y+d13.x);
; }
; __device__ __forceinline__ void phase_hyena(KP kp_, int hf){ asm volatile("" : "+s"(kp_)); const Params p=load_params(kp_);
;     ...
;         if (st==1){ int tq=tid; asm volatile("" : "+v"(tq));
;           _Pragma("unroll 4") for (int i=0;i<8;++i){ int tb=tq+512*i; float2 xr[2]; inv12_half(Z,twA,twB,tb,xr[0],xr[1]);
;             _Pragma("unroll") for (int hh=0;hh<2;++hh){ int t=tb+hh*4096;
;               float u0=hconv3(rv,t,wv0,wv1,wv2,bv_), u1=hconv3(rv+8192,t,wv0,wv1,wv2,bv_);
;               float x0=hconv3(r1,t,wa0,wa1,wa2,ba_), x1=hconv3(r1+8192,t,wa0,wa1,wa2,ba_);
;               float2 y=xr[hh]; y.x*=(1.f/16384.f); y.y*=(1.f/16384.f);
;               Zs[t]=make_float2(x0*(y.x+u0*bias0), x1*(y.y+u1*bias0)); } }
	v_pk_mul_f32 v[222:223], v[58:59], v[10:11] op_sel:[1,1] op_sel_hi:[1,0]
	v_pk_fma_f32 v[22:23], v[58:59], v[10:11], v[222:223] op_sel:[0,0,0] op_sel_hi:[0,1,1] neg_lo:[0,0,1]
	v_pk_mul_f32 v[222:223], v[22:23], v[22:23] op_sel:[1,1] op_sel_hi:[1,0]
	v_pk_fma_f32 v[24:25], v[22:23], v[22:23], v[222:223] op_sel:[0,0,0] op_sel_hi:[0,1,1] neg_lo:[0,0,1]
	v_pk_mul_f32 v[222:223], v[24:25], v[22:23] op_sel:[1,1] op_sel_hi:[1,0]
	v_pk_fma_f32 v[26:27], v[24:25], v[22:23], v[222:223] op_sel:[0,0,0] op_sel_hi:[0,1,1] neg_lo:[0,0,1]
	v_pk_mul_f32 v[222:223], v[62:63], v[22:23] op_sel:[1,1] op_sel_hi:[0,1]
	v_pk_fma_f32 v[28:29], v[62:63], v[22:23], v[222:223] op_sel:[0,0,0] op_sel_hi:[1,0,1] neg_hi:[0,0,1]
	v_pk_mul_f32 v[222:223], v[64:65], v[24:25] op_sel:[1,1] op_sel_hi:[0,1]
	v_pk_fma_f32 v[30:31], v[64:65], v[24:25], v[222:223] op_sel:[0,0,0] op_sel_hi:[1,0,1] neg_hi:[0,0,1]
	v_pk_mul_f32 v[222:223], v[66:67], v[26:27] op_sel:[1,1] op_sel_hi:[0,1]
	v_pk_fma_f32 v[68:69], v[66:67], v[26:27], v[222:223] op_sel:[0,0,0] op_sel_hi:[1,0,1] neg_hi:[0,0,1]
	v_pk_add_f32 v[70:71], v[60:61], v[30:31]
	v_pk_add_f32 v[72:73], v[60:61], v[30:31] neg_lo:[0,1] neg_hi:[0,1]
	v_pk_add_f32 v[74:75], v[28:29], v[68:69]
	v_pk_add_f32 v[80:81], v[28:29], v[68:69] neg_lo:[0,1] neg_hi:[0,1]
	v_pk_add_f32 v[82:83], v[70:71], v[74:75]
	v_pk_add_f32 v[84:85], v[72:73], v[80:81] op_sel:[0,1] op_sel_hi:[1,0] neg_lo:[0,1]
	s_waitcnt vmcnt(10)
	v_lshlrev_b32_e32 v224, 16, v240
	v_lshlrev_b32_e32 v225, 16, v241
	v_mov_b32_e32 v226, 0
	v_mov_b32_e32 v227, 0
	v_mov_b32_e32 v110, 0
	v_mov_b32_e32 v111, 0
	v_mov_b32_dpp v226, v224 wave_shr:1 row_mask:0xf bank_mask:0xf
	v_mov_b32_dpp v227, v225 wave_shr:1 row_mask:0xf bank_mask:0xf
	v_mov_b32_dpp v110, v224 wave_shl:1 row_mask:0xf bank_mask:0xf
	v_mov_b32_dpp v111, v225 wave_shl:1 row_mask:0xf bank_mask:0xf
	v_pk_mul_f32 v[112:113], v[34:35], v[224:225]
	v_pk_fma_f32 v[112:113], v[32:33], v[226:227], v[112:113]
	v_pk_fma_f32 v[112:113], v[36:37], v[110:111], v[112:113]
	v_pk_add_f32 v[114:115], v[38:39], v[112:113]
	v_lshlrev_b32_e32 v224, 16, v242
	v_lshlrev_b32_e32 v225, 16, v243
	v_mov_b32_e32 v226, 0
	v_mov_b32_e32 v227, 0
	v_mov_b32_e32 v110, 0
	v_mov_b32_e32 v111, 0
	v_mov_b32_dpp v226, v224 wave_shr:1 row_mask:0xf bank_mask:0xf
	v_mov_b32_dpp v227, v225 wave_shr:1 row_mask:0xf bank_mask:0xf
	v_mov_b32_dpp v110, v224 wave_shl:1 row_mask:0xf bank_mask:0xf
	v_mov_b32_dpp v111, v225 wave_shl:1 row_mask:0xf bank_mask:0xf
	v_pk_mul_f32 v[112:113], v[42:43], v[224:225]
	v_pk_fma_f32 v[112:113], v[40:41], v[226:227], v[112:113]
	v_pk_fma_f32 v[112:113], v[44:45], v[110:111], v[112:113]
	v_pk_add_f32 v[156:157], v[46:47], v[112:113]
	v_lshlrev_b32_e32 v224, 16, v244
	v_lshlrev_b32_e32 v225, 16, v245
	v_mov_b32_e32 v226, 0
	v_mov_b32_e32 v227, 0
	v_mov_b32_e32 v110, 0
	v_mov_b32_e32 v111, 0
	v_mov_b32_dpp v226, v224 wave_shr:1 row_mask:0xf bank_mask:0xf
	v_mov_b32_dpp v227, v225 wave_shr:1 row_mask:0xf bank_mask:0xf
	v_mov_b32_dpp v110, v224 wave_shl:1 row_mask:0xf bank_mask:0xf
	v_mov_b32_dpp v111, v225 wave_shl:1 row_mask:0xf bank_mask:0xf
	v_pk_mul_f32 v[112:113], v[34:35], v[224:225]
	v_pk_fma_f32 v[112:113], v[32:33], v[226:227], v[112:113]
	v_pk_fma_f32 v[112:113], v[36:37], v[110:111], v[112:113]
	v_pk_add_f32 v[116:117], v[38:39], v[112:113]
	v_lshlrev_b32_e32 v224, 16, v246
	v_lshlrev_b32_e32 v225, 16, v247
	v_mov_b32_e32 v226, 0
	v_mov_b32_e32 v227, 0
	v_mov_b32_e32 v110, 0
	v_mov_b32_e32 v111, 0
	v_mov_b32_dpp v226, v224 wave_shr:1 row_mask:0xf bank_mask:0xf
	v_mov_b32_dpp v227, v225 wave_shr:1 row_mask:0xf bank_mask:0xf
	v_mov_b32_dpp v110, v224 wave_shl:1 row_mask:0xf bank_mask:0xf
	v_mov_b32_dpp v111, v225 wave_shl:1 row_mask:0xf bank_mask:0xf
	v_pk_mul_f32 v[112:113], v[42:43], v[224:225]
	v_pk_fma_f32 v[112:113], v[40:41], v[226:227], v[112:113]
	v_pk_fma_f32 v[112:113], v[44:45], v[110:111], v[112:113]
	v_pk_add_f32 v[158:159], v[46:47], v[112:113]
	v_pk_mul_f32 v[114:115], v[48:49], v[114:115]
	v_pk_fma_f32 v[82:83], v[82:83], s[66:67], v[114:115] op_sel_hi:[1,0,1]
	v_pk_mul_f32 v[82:83], v[82:83], v[156:157]
	v_add_u32_e32 v6, 0x3000, v5
	global_store_dwordx2 v6, v[82:83], s[80:81]
	v_pk_mul_f32 v[116:117], v[48:49], v[116:117]
	v_pk_fma_f32 v[84:85], v[84:85], s[66:67], v[116:117] op_sel_hi:[1,0,1]
	v_pk_mul_f32 v[84:85], v[84:85], v[158:159]
	v_add_u32_e32 v6, 0xb000, v5
	global_store_dwordx2 v6, v[84:85], s[80:81]
	global_load_ushort v240, v135, s[12:13] offset:1024
	global_load_ushort v241, v139, s[12:13] offset:1024
	global_load_ushort v242, v143, s[12:13] offset:1024
	global_load_ushort v243, v151, s[12:13] offset:1024
	global_load_ushort v244, v137, s[12:13] offset:1024
	global_load_ushort v245, v141, s[12:13] offset:1024
	global_load_ushort v246, v145, s[12:13] offset:1024
	global_load_ushort v247, v153, s[12:13] offset:1024
	ds_read_b64 v[58:59], v7 offset:320
	ds_read_b64 v[60:61], v8 offset:20480
	ds_read_b64 v[62:63], v8 offset:53248
	ds_read_b64 v[64:65], v9 offset:20480
	ds_read_b64 v[66:67], v9 offset:53248
	s_waitcnt lgkmcnt(5)
; HD float2 cmul(float2 a, float2 b){ return make_float2(a.x*b.x - a.y*b.y, a.x*b.y + a.y*b.x); }
; HD float2 cmulc(float2 a, float2 b){ return make_float2(a.x*b.x + a.y*b.y, a.y*b.x - a.x*b.y); }
; HD void inv12_half(const float2* Z, const float2* twA, const float2* twB, int t, float2& x0, float2& x1){
;   float2 w1=cmul(twA[t>>6],twB[t&63]), w2=cmul(w1,w1), w3=cmul(w2,w1);
;   float2 b0=Z[t], b1=cmulc(Z[t+4096],w1), b2=cmulc(Z[t+8192],w2), b3=cmulc(Z[t+12288],w3);
;   float2 s02=make_float2(b0.x+b2.x,b0.y+b2.y), d02=make_float2(b0.x-b2.x,b0.y-b2.y);
;   float2 s13=make_float2(b1.x+b3.x,b1.y+b3.y), d13=make_float2(b1.x-b3.x,b1.y-b3.y);
;   x0=make_float2(s02.x+s13.x,s02.y+s13.y);
;   x1=make_float2(d02.x-d13.y,d02.y+d13.x);
; }
; __device__ __forceinline__ void phase_hyena(KP kp_, int hf){ asm volatile("" : "+s"(kp_)); const Params p=load_params(kp_);
;     ...
;         if (st==1){ int tq=tid; asm volatile("" : "+v"(tq));
;           _Pragma("unroll 4") for (int i=0;i<8;++i){ int tb=tq+512*i; float2 xr[2]; inv12_half(Z,twA,twB,tb,xr[0],xr[1]);
;             _Pragma("unroll") for (int hh=0;hh<2;++hh){ int t=tb+hh*4096;
;               float u0=hconv3(rv,t,wv0,wv1,wv2,bv_), u1=hconv3(rv+8192,t,wv0,wv1,wv2,bv_);
;               float x0=hconv3(r1,t,wa0,wa1,wa2,ba_), x1=hconv3(r1+8192,t,wa0,wa1,wa2,ba_);
;               float2 y=xr[hh]; y.x*=(1.f/16384.f); y.y*=(1.f/16384.f);
;               Zs[t]=make_float2(x0*(y.x+u0*bias0), x1*(y.y+u1*bias0)); } }
	v_pk_mul_f32 v[222:223], v[12:13], v[10:11] op_sel:[1,1] op_sel_hi:[1,0]
	v_pk_fma_f32 v[22:23], v[12:13], v[10:11], v[222:223] op_sel:[0,0,0] op_sel_hi:[0,1,1] neg_lo:[0,0,1]
	v_pk_mul_f32 v[222:223], v[22:23], v[22:23] op_sel:[1,1] op_sel_hi:[1,0]
	v_pk_fma_f32 v[24:25], v[22:23], v[22:23], v[222:223] op_sel:[0,0,0] op_sel_hi:[0,1,1] neg_lo:[0,0,1]
	v_pk_mul_f32 v[222:223], v[24:25], v[22:23] op_sel:[1,1] op_sel_hi:[1,0]
	v_pk_fma_f32 v[26:27], v[24:25], v[22:23], v[222:223] op_sel:[0,0,0] op_sel_hi:[0,1,1] neg_lo:[0,0,1]
	v_pk_mul_f32 v[222:223], v[16:17], v[22:23] op_sel:[1,1] op_sel_hi:[0,1]
	v_pk_fma_f32 v[28:29], v[16:17], v[22:23], v[222:223] op_sel:[0,0,0] op_sel_hi:[1,0,1] neg_hi:[0,0,1]
	v_pk_mul_f32 v[222:223], v[18:19], v[24:25] op_sel:[1,1] op_sel_hi:[0,1]
	v_pk_fma_f32 v[30:31], v[18:19], v[24:25], v[222:223] op_sel:[0,0,0] op_sel_hi:[1,0,1] neg_hi:[0,0,1]
	v_pk_mul_f32 v[222:223], v[20:21], v[26:27] op_sel:[1,1] op_sel_hi:[0,1]
	v_pk_fma_f32 v[68:69], v[20:21], v[26:27], v[222:223] op_sel:[0,0,0] op_sel_hi:[1,0,1] neg_hi:[0,0,1]
	v_pk_add_f32 v[70:71], v[14:15], v[30:31]
	v_pk_add_f32 v[72:73], v[14:15], v[30:31] neg_lo:[0,1] neg_hi:[0,1]
	v_pk_add_f32 v[74:75], v[28:29], v[68:69]
	v_pk_add_f32 v[80:81], v[28:29], v[68:69] neg_lo:[0,1] neg_hi:[0,1]
	v_pk_add_f32 v[82:83], v[70:71], v[74:75]
	v_pk_add_f32 v[84:85], v[72:73], v[80:81] op_sel:[0,1] op_sel_hi:[1,0] neg_lo:[0,1]
	s_waitcnt vmcnt(10)
	v_lshlrev_b32_e32 v224, 16, v228
	v_lshlrev_b32_e32 v225, 16, v229
	v_mov_b32_e32 v226, 0
	v_mov_b32_e32 v227, 0
	v_mov_b32_e32 v110, 0
	v_mov_b32_e32 v111, 0
	v_mov_b32_dpp v226, v224 wave_shr:1 row_mask:0xf bank_mask:0xf
	v_mov_b32_dpp v227, v225 wave_shr:1 row_mask:0xf bank_mask:0xf
	v_mov_b32_dpp v110, v224 wave_shl:1 row_mask:0xf bank_mask:0xf
	v_mov_b32_dpp v111, v225 wave_shl:1 row_mask:0xf bank_mask:0xf
	v_pk_mul_f32 v[112:113], v[34:35], v[224:225]
	v_pk_fma_f32 v[112:113], v[32:33], v[226:227], v[112:113]
	v_pk_fma_f32 v[112:113], v[36:37], v[110:111], v[112:113]
	v_pk_add_f32 v[114:115], v[38:39], v[112:113]
	v_lshlrev_b32_e32 v224, 16, v230
	v_lshlrev_b32_e32 v225, 16, v231
	v_mov_b32_e32 v226, 0
	v_mov_b32_e32 v227, 0
	v_mov_b32_e32 v110, 0
	v_mov_b32_e32 v111, 0
	v_mov_b32_dpp v226, v224 wave_shr:1 row_mask:0xf bank_mask:0xf
	v_mov_b32_dpp v227, v225 wave_shr:1 row_mask:0xf bank_mask:0xf
	v_mov_b32_dpp v110, v224 wave_shl:1 row_mask:0xf bank_mask:0xf
	v_mov_b32_dpp v111, v225 wave_shl:1 row_mask:0xf bank_mask:0xf
	v_pk_mul_f32 v[112:113], v[42:43], v[224:225]
	v_pk_fma_f32 v[112:113], v[40:41], v[226:227], v[112:113]
	v_pk_fma_f32 v[112:113], v[44:45], v[110:111], v[112:113]
	v_pk_add_f32 v[156:157], v[46:47], v[112:113]
	v_lshlrev_b32_e32 v224, 16, v232
	v_lshlrev_b32_e32 v225, 16, v233
	v_mov_b32_e32 v226, 0
	v_mov_b32_e32 v227, 0
	v_mov_b32_e32 v110, 0
	v_mov_b32_e32 v111, 0
	v_mov_b32_dpp v226, v224 wave_shr:1 row_mask:0xf bank_mask:0xf
	v_mov_b32_dpp v227, v225 wave_shr:1 row_mask:0xf bank_mask:0xf
	v_mov_b32_dpp v110, v224 wave_shl:1 row_mask:0xf bank_mask:0xf
	v_mov_b32_dpp v111, v225 wave_shl:1 row_mask:0xf bank_mask:0xf
	v_pk_mul_f32 v[112:113], v[34:35], v[224:225]
	v_pk_fma_f32 v[112:113], v[32:33], v[226:227], v[112:113]
	v_pk_fma_f32 v[112:113], v[36:37], v[110:111], v[112:113]
	v_pk_add_f32 v[116:117], v[38:39], v[112:113]
	v_lshlrev_b32_e32 v224, 16, v234
	v_lshlrev_b32_e32 v225, 16, v235
	v_mov_b32_e32 v226, 0
	v_mov_b32_e32 v227, 0
	v_mov_b32_e32 v110, 0
	v_mov_b32_e32 v111, 0
	v_mov_b32_dpp v226, v224 wave_shr:1 row_mask:0xf bank_mask:0xf
	v_mov_b32_dpp v227, v225 wave_shr:1 row_mask:0xf bank_mask:0xf
	v_mov_b32_dpp v110, v224 wave_shl:1 row_mask:0xf bank_mask:0xf
	v_mov_b32_dpp v111, v225 wave_shl:1 row_mask:0xf bank_mask:0xf
	v_pk_mul_f32 v[112:113], v[42:43], v[224:225]
	v_pk_fma_f32 v[112:113], v[40:41], v[226:227], v[112:113]
	v_pk_fma_f32 v[112:113], v[44:45], v[110:111], v[112:113]
	v_pk_add_f32 v[158:159], v[46:47], v[112:113]
	v_pk_mul_f32 v[114:115], v[48:49], v[114:115]
	v_pk_fma_f32 v[82:83], v[82:83], s[66:67], v[114:115] op_sel_hi:[1,0,1]
	v_pk_mul_f32 v[82:83], v[82:83], v[156:157]
	v_add_u32_e32 v6, 0x4000, v5
	global_store_dwordx2 v6, v[82:83], s[80:81]
	v_pk_mul_f32 v[116:117], v[48:49], v[116:117]
	v_pk_fma_f32 v[84:85], v[84:85], s[66:67], v[116:117] op_sel_hi:[1,0,1]
	v_pk_mul_f32 v[84:85], v[84:85], v[158:159]
	v_add_u32_e32 v6, 0xc000, v5
	global_store_dwordx2 v6, v[84:85], s[80:81]
	global_load_ushort v228, v135, s[12:13] offset:2048
	global_load_ushort v229, v139, s[12:13] offset:2048
	global_load_ushort v230, v143, s[12:13] offset:2048
	global_load_ushort v231, v151, s[12:13] offset:2048
	global_load_ushort v232, v137, s[12:13] offset:2048
	global_load_ushort v233, v141, s[12:13] offset:2048
	global_load_ushort v234, v145, s[12:13] offset:2048
	global_load_ushort v235, v153, s[12:13] offset:2048
	ds_read_b64 v[12:13], v7 offset:384
	ds_read_b64 v[14:15], v8 offset:24576
	ds_read_b64 v[16:17], v8 offset:57344
	ds_read_b64 v[18:19], v9 offset:24576
	ds_read_b64 v[20:21], v9 offset:57344
	s_waitcnt lgkmcnt(5)
; HD float2 cmul(float2 a, float2 b){ return make_float2(a.x*b.x - a.y*b.y, a.x*b.y + a.y*b.x); }
; HD float2 cmulc(float2 a, float2 b){ return make_float2(a.x*b.x + a.y*b.y, a.y*b.x - a.x*b.y); }
; HD void inv12_half(const float2* Z, const float2* twA, const float2* twB, int t, float2& x0, float2& x1){
;   float2 w1=cmul(twA[t>>6],twB[t&63]), w2=cmul(w1,w1), w3=cmul(w2,w1);
;   float2 b0=Z[t], b1=cmulc(Z[t+4096],w1), b2=cmulc(Z[t+8192],w2), b3=cmulc(Z[t+12288],w3);
;   float2 s02=make_float2(b0.x+b2.x,b0.y+b2.y), d02=make_float2(b0.x-b2.x,b0.y-b2.y);
;   float2 s13=make_float2(b1.x+b3.x,b1.y+b3.y), d13=make_float2(b1.x-b3.x,b1.y-b3.y);
;   x0=make_float2(s02.x+s13.x,s02.y+s13.y);
;   x1=make_float2(d02.x-d13.y,d02.y+d13.x);
; }
; __device__ __forceinline__ void phase_hyena(KP kp_, int hf){ asm volatile("" : "+s"(kp_)); const Params p=load_params(kp_);
;     ...
;         if (st==1){ int tq=tid; asm volatile("" : "+v"(tq));
;           _Pragma("unroll 4") for (int i=0;i<8;++i){ int tb=tq+512*i; float2 xr[2]; inv12_half(Z,twA,twB,tb,xr[0],xr[1]);
;             _Pragma("unroll") for (int hh=0;hh<2;++hh){ int t=tb+hh*4096;
;               float u0=hconv3(rv,t,wv0,wv1,wv2,bv_), u1=hconv3(rv+8192,t,wv0,wv1,wv2,bv_);
;               float x0=hconv3(r1,t,wa0,wa1,wa2,ba_), x1=hconv3(r1+8192,t,wa0,wa1,wa2,ba_);
;               float2 y=xr[hh]; y.x*=(1.f/16384.f); y.y*=(1.f/16384.f);
;               Zs[t]=make_float2(x0*(y.x+u0*bias0), x1*(y.y+u1*bias0)); } }
	v_pk_mul_f32 v[222:223], v[58:59], v[10:11] op_sel:[1,1] op_sel_hi:[1,0]
	v_pk_fma_f32 v[22:23], v[58:59], v[10:11], v[222:223] op_sel:[0,0,0] op_sel_hi:[0,1,1] neg_lo:[0,0,1]
	v_pk_mul_f32 v[222:223], v[22:23], v[22:23] op_sel:[1,1] op_sel_hi:[1,0]
	v_pk_fma_f32 v[24:25], v[22:23], v[22:23], v[222:223] op_sel:[0,0,0] op_sel_hi:[0,1,1] neg_lo:[0,0,1]
	v_pk_mul_f32 v[222:223], v[24:25], v[22:23] op_sel:[1,1] op_sel_hi:[1,0]
	v_pk_fma_f32 v[26:27], v[24:25], v[22:23], v[222:223] op_sel:[0,0,0] op_sel_hi:[0,1,1] neg_lo:[0,0,1]
	v_pk_mul_f32 v[222:223], v[62:63], v[22:23] op_sel:[1,1] op_sel_hi:[0,1]
	v_pk_fma_f32 v[28:29], v[62:63], v[22:23], v[222:223] op_sel:[0,0,0] op_sel_hi:[1,0,1] neg_hi:[0,0,1]
	v_pk_mul_f32 v[222:223], v[64:65], v[24:25] op_sel:[1,1] op_sel_hi:[0,1]
	v_pk_fma_f32 v[30:31], v[64:65], v[24:25], v[222:223] op_sel:[0,0,0] op_sel_hi:[1,0,1] neg_hi:[0,0,1]
	v_pk_mul_f32 v[222:223], v[66:67], v[26:27] op_sel:[1,1] op_sel_hi:[0,1]
	v_pk_fma_f32 v[68:69], v[66:67], v[26:27], v[222:223] op_sel:[0,0,0] op_sel_hi:[1,0,1] neg_hi:[0,0,1]
	v_pk_add_f32 v[70:71], v[60:61], v[30:31]
	v_pk_add_f32 v[72:73], v[60:61], v[30:31] neg_lo:[0,1] neg_hi:[0,1]
	v_pk_add_f32 v[74:75], v[28:29], v[68:69]
	v_pk_add_f32 v[80:81], v[28:29], v[68:69] neg_lo:[0,1] neg_hi:[0,1]
	v_pk_add_f32 v[82:83], v[70:71], v[74:75]
	v_pk_add_f32 v[84:85], v[72:73], v[80:81] op_sel:[0,1] op_sel_hi:[1,0] neg_lo:[0,1]
	s_waitcnt vmcnt(10)
	v_lshlrev_b32_e32 v224, 16, v240
	v_lshlrev_b32_e32 v225, 16, v241
	v_mov_b32_e32 v226, 0
	v_mov_b32_e32 v227, 0
	v_mov_b32_e32 v110, 0
	v_mov_b32_e32 v111, 0
	v_mov_b32_dpp v226, v224 wave_shr:1 row_mask:0xf bank_mask:0xf
	v_mov_b32_dpp v227, v225 wave_shr:1 row_mask:0xf bank_mask:0xf
	v_mov_b32_dpp v110, v224 wave_shl:1 row_mask:0xf bank_mask:0xf
	v_mov_b32_dpp v111, v225 wave_shl:1 row_mask:0xf bank_mask:0xf
	v_pk_mul_f32 v[112:113], v[34:35], v[224:225]
	v_pk_fma_f32 v[112:113], v[32:33], v[226:227], v[112:113]
	v_pk_fma_f32 v[112:113], v[36:37], v[110:111], v[112:113]
	v_pk_add_f32 v[114:115], v[38:39], v[112:113]
	v_lshlrev_b32_e32 v224, 16, v242
	v_lshlrev_b32_e32 v225, 16, v243
	v_mov_b32_e32 v226, 0
	v_mov_b32_e32 v227, 0
	v_mov_b32_e32 v110, 0
	v_mov_b32_e32 v111, 0
	v_mov_b32_dpp v226, v224 wave_shr:1 row_mask:0xf bank_mask:0xf
	v_mov_b32_dpp v227, v225 wave_shr:1 row_mask:0xf bank_mask:0xf
	v_mov_b32_dpp v110, v224 wave_shl:1 row_mask:0xf bank_mask:0xf
	v_mov_b32_dpp v111, v225 wave_shl:1 row_mask:0xf bank_mask:0xf
	v_pk_mul_f32 v[112:113], v[42:43], v[224:225]
	v_pk_fma_f32 v[112:113], v[40:41], v[226:227], v[112:113]
	v_pk_fma_f32 v[112:113], v[44:45], v[110:111], v[112:113]
	v_pk_add_f32 v[156:157], v[46:47], v[112:113]
	v_lshlrev_b32_e32 v224, 16, v244
	v_lshlrev_b32_e32 v225, 16, v245
	v_mov_b32_e32 v226, 0
	v_mov_b32_e32 v227, 0
	v_mov_b32_e32 v110, 0
	v_mov_b32_e32 v111, 0
	v_mov_b32_dpp v226, v224 wave_shr:1 row_mask:0xf bank_mask:0xf
	v_mov_b32_dpp v227, v225 wave_shr:1 row_mask:0xf bank_mask:0xf
	v_mov_b32_dpp v110, v224 wave_shl:1 row_mask:0xf bank_mask:0xf
	v_mov_b32_dpp v111, v225 wave_shl:1 row_mask:0xf bank_mask:0xf
	v_pk_mul_f32 v[112:113], v[34:35], v[224:225]
	v_pk_fma_f32 v[112:113], v[32:33], v[226:227], v[112:113]
	v_pk_fma_f32 v[112:113], v[36:37], v[110:111], v[112:113]
	v_pk_add_f32 v[116:117], v[38:39], v[112:113]
	v_lshlrev_b32_e32 v224, 16, v246
	v_lshlrev_b32_e32 v225, 16, v247
	v_mov_b32_e32 v226, 0
	v_mov_b32_e32 v227, 0
	v_mov_b32_e32 v110, 0
	v_mov_b32_e32 v111, 0
	v_mov_b32_dpp v226, v224 wave_shr:1 row_mask:0xf bank_mask:0xf
	v_mov_b32_dpp v227, v225 wave_shr:1 row_mask:0xf bank_mask:0xf
	v_mov_b32_dpp v110, v224 wave_shl:1 row_mask:0xf bank_mask:0xf
	v_mov_b32_dpp v111, v225 wave_shl:1 row_mask:0xf bank_mask:0xf
	v_pk_mul_f32 v[112:113], v[42:43], v[224:225]
	v_pk_fma_f32 v[112:113], v[40:41], v[226:227], v[112:113]
	v_pk_fma_f32 v[112:113], v[44:45], v[110:111], v[112:113]
	v_pk_add_f32 v[158:159], v[46:47], v[112:113]
	v_pk_mul_f32 v[114:115], v[48:49], v[114:115]
	v_pk_fma_f32 v[82:83], v[82:83], s[66:67], v[114:115] op_sel_hi:[1,0,1]
	v_pk_mul_f32 v[82:83], v[82:83], v[156:157]
	v_add_u32_e32 v6, 0x5000, v5
	global_store_dwordx2 v6, v[82:83], s[80:81]
	v_pk_mul_f32 v[116:117], v[48:49], v[116:117]
	v_pk_fma_f32 v[84:85], v[84:85], s[66:67], v[116:117] op_sel_hi:[1,0,1]
	v_pk_mul_f32 v[84:85], v[84:85], v[158:159]
	v_add_u32_e32 v6, 0xd000, v5
	global_store_dwordx2 v6, v[84:85], s[80:81]
	global_load_ushort v240, v135, s[12:13] offset:3072
	global_load_ushort v241, v139, s[12:13] offset:3072
	global_load_ushort v242, v143, s[12:13] offset:3072
	global_load_ushort v243, v151, s[12:13] offset:3072
	global_load_ushort v244, v137, s[12:13] offset:3072
	global_load_ushort v245, v141, s[12:13] offset:3072
	global_load_ushort v246, v145, s[12:13] offset:3072
	global_load_ushort v247, v153, s[12:13] offset:3072
	ds_read_b64 v[58:59], v7 offset:448
	ds_read_b64 v[60:61], v8 offset:28672
	ds_read_b64 v[62:63], v8 offset:61440
	ds_read_b64 v[64:65], v9 offset:28672
	ds_read_b64 v[66:67], v9 offset:61440
	s_waitcnt lgkmcnt(5)
; HD float2 cmul(float2 a, float2 b){ return make_float2(a.x*b.x - a.y*b.y, a.x*b.y + a.y*b.x); }
; HD float2 cmulc(float2 a, float2 b){ return make_float2(a.x*b.x + a.y*b.y, a.y*b.x - a.x*b.y); }
; HD void inv12_half(const float2* Z, const float2* twA, const float2* twB, int t, float2& x0, float2& x1){
;   float2 w1=cmul(twA[t>>6],twB[t&63]), w2=cmul(w1,w1), w3=cmul(w2,w1);
;   float2 b0=Z[t], b1=cmulc(Z[t+4096],w1), b2=cmulc(Z[t+8192],w2), b3=cmulc(Z[t+12288],w3);
;   float2 s02=make_float2(b0.x+b2.x,b0.y+b2.y), d02=make_float2(b0.x-b2.x,b0.y-b2.y);
;   float2 s13=make_float2(b1.x+b3.x,b1.y+b3.y), d13=make_float2(b1.x-b3.x,b1.y-b3.y);
;   x0=make_float2(s02.x+s13.x,s02.y+s13.y);
;   x1=make_float2(d02.x-d13.y,d02.y+d13.x);
; }
; __device__ __forceinline__ void phase_hyena(KP kp_, int hf){ asm volatile("" : "+s"(kp_)); const Params p=load_params(kp_);
;     ...
;         if (st==1){ int tq=tid; asm volatile("" : "+v"(tq));
;           _Pragma("unroll 4") for (int i=0;i<8;++i){ int tb=tq+512*i; float2 xr[2]; inv12_half(Z,twA,twB,tb,xr[0],xr[1]);
;             _Pragma("unroll") for (int hh=0;hh<2;++hh){ int t=tb+hh*4096;
;               float u0=hconv3(rv,t,wv0,wv1,wv2,bv_), u1=hconv3(rv+8192,t,wv0,wv1,wv2,bv_);
;               float x0=hconv3(r1,t,wa0,wa1,wa2,ba_), x1=hconv3(r1+8192,t,wa0,wa1,wa2,ba_);
;               float2 y=xr[hh]; y.x*=(1.f/16384.f); y.y*=(1.f/16384.f);
;               Zs[t]=make_float2(x0*(y.x+u0*bias0), x1*(y.y+u1*bias0)); } }
	v_pk_mul_f32 v[222:223], v[12:13], v[10:11] op_sel:[1,1] op_sel_hi:[1,0]
	v_pk_fma_f32 v[22:23], v[12:13], v[10:11], v[222:223] op_sel:[0,0,0] op_sel_hi:[0,1,1] neg_lo:[0,0,1]
	v_pk_mul_f32 v[222:223], v[22:23], v[22:23] op_sel:[1,1] op_sel_hi:[1,0]
	v_pk_fma_f32 v[24:25], v[22:23], v[22:23], v[222:223] op_sel:[0,0,0] op_sel_hi:[0,1,1] neg_lo:[0,0,1]
	v_pk_mul_f32 v[222:223], v[24:25], v[22:23] op_sel:[1,1] op_sel_hi:[1,0]
	v_pk_fma_f32 v[26:27], v[24:25], v[22:23], v[222:223] op_sel:[0,0,0] op_sel_hi:[0,1,1] neg_lo:[0,0,1]
	v_pk_mul_f32 v[222:223], v[16:17], v[22:23] op_sel:[1,1] op_sel_hi:[0,1]
	v_pk_fma_f32 v[28:29], v[16:17], v[22:23], v[222:223] op_sel:[0,0,0] op_sel_hi:[1,0,1] neg_hi:[0,0,1]
	v_pk_mul_f32 v[222:223], v[18:19], v[24:25] op_sel:[1,1] op_sel_hi:[0,1]
	v_pk_fma_f32 v[30:31], v[18:19], v[24:25], v[222:223] op_sel:[0,0,0] op_sel_hi:[1,0,1] neg_hi:[0,0,1]
	v_pk_mul_f32 v[222:223], v[20:21], v[26:27] op_sel:[1,1] op_sel_hi:[0,1]
	v_pk_fma_f32 v[68:69], v[20:21], v[26:27], v[222:223] op_sel:[0,0,0] op_sel_hi:[1,0,1] neg_hi:[0,0,1]
	v_pk_add_f32 v[70:71], v[14:15], v[30:31]
	v_pk_add_f32 v[72:73], v[14:15], v[30:31] neg_lo:[0,1] neg_hi:[0,1]
	v_pk_add_f32 v[74:75], v[28:29], v[68:69]
	v_pk_add_f32 v[80:81], v[28:29], v[68:69] neg_lo:[0,1] neg_hi:[0,1]
	v_pk_add_f32 v[82:83], v[70:71], v[74:75]
	v_pk_add_f32 v[84:85], v[72:73], v[80:81] op_sel:[0,1] op_sel_hi:[1,0] neg_lo:[0,1]
	s_waitcnt vmcnt(10)
	v_lshlrev_b32_e32 v224, 16, v228
	v_lshlrev_b32_e32 v225, 16, v229
	v_mov_b32_e32 v226, 0
	v_mov_b32_e32 v227, 0
	v_mov_b32_e32 v110, 0
	v_mov_b32_e32 v111, 0
	v_mov_b32_dpp v226, v224 wave_shr:1 row_mask:0xf bank_mask:0xf
	v_mov_b32_dpp v227, v225 wave_shr:1 row_mask:0xf bank_mask:0xf
	v_mov_b32_dpp v110, v224 wave_shl:1 row_mask:0xf bank_mask:0xf
	v_mov_b32_dpp v111, v225 wave_shl:1 row_mask:0xf bank_mask:0xf
	v_pk_mul_f32 v[112:113], v[34:35], v[224:225]
	v_pk_fma_f32 v[112:113], v[32:33], v[226:227], v[112:113]
	v_pk_fma_f32 v[112:113], v[36:37], v[110:111], v[112:113]
	v_pk_add_f32 v[114:115], v[38:39], v[112:113]
	v_lshlrev_b32_e32 v224, 16, v230
	v_lshlrev_b32_e32 v225, 16, v231
	v_mov_b32_e32 v226, 0
	v_mov_b32_e32 v227, 0
	v_mov_b32_e32 v110, 0
	v_mov_b32_e32 v111, 0
	v_mov_b32_dpp v226, v224 wave_shr:1 row_mask:0xf bank_mask:0xf
	v_mov_b32_dpp v227, v225 wave_shr:1 row_mask:0xf bank_mask:0xf
	v_mov_b32_dpp v110, v224 wave_shl:1 row_mask:0xf bank_mask:0xf
	v_mov_b32_dpp v111, v225 wave_shl:1 row_mask:0xf bank_mask:0xf
	v_pk_mul_f32 v[112:113], v[42:43], v[224:225]
	v_pk_fma_f32 v[112:113], v[40:41], v[226:227], v[112:113]
	v_pk_fma_f32 v[112:113], v[44:45], v[110:111], v[112:113]
	v_pk_add_f32 v[156:157], v[46:47], v[112:113]
	v_lshlrev_b32_e32 v224, 16, v232
	v_lshlrev_b32_e32 v225, 16, v233
	v_mov_b32_e32 v226, 0
	v_mov_b32_e32 v227, 0
	v_mov_b32_e32 v110, 0
	v_mov_b32_e32 v111, 0
	v_mov_b32_dpp v226, v224 wave_shr:1 row_mask:0xf bank_mask:0xf
	v_mov_b32_dpp v227, v225 wave_shr:1 row_mask:0xf bank_mask:0xf
	v_mov_b32_dpp v110, v224 wave_shl:1 row_mask:0xf bank_mask:0xf
	v_mov_b32_dpp v111, v225 wave_shl:1 row_mask:0xf bank_mask:0xf
	v_pk_mul_f32 v[112:113], v[34:35], v[224:225]
	v_pk_fma_f32 v[112:113], v[32:33], v[226:227], v[112:113]
	v_pk_fma_f32 v[112:113], v[36:37], v[110:111], v[112:113]
	v_pk_add_f32 v[116:117], v[38:39], v[112:113]
	v_lshlrev_b32_e32 v224, 16, v234
	v_lshlrev_b32_e32 v225, 16, v235
	v_mov_b32_e32 v226, 0
	v_mov_b32_e32 v227, 0
	v_mov_b32_e32 v110, 0
	v_mov_b32_e32 v111, 0
	v_mov_b32_dpp v226, v224 wave_shr:1 row_mask:0xf bank_mask:0xf
	v_mov_b32_dpp v227, v225 wave_shr:1 row_mask:0xf bank_mask:0xf
	v_mov_b32_dpp v110, v224 wave_shl:1 row_mask:0xf bank_mask:0xf
	v_mov_b32_dpp v111, v225 wave_shl:1 row_mask:0xf bank_mask:0xf
	v_pk_mul_f32 v[112:113], v[42:43], v[224:225]
	v_pk_fma_f32 v[112:113], v[40:41], v[226:227], v[112:113]
	v_pk_fma_f32 v[112:113], v[44:45], v[110:111], v[112:113]
	v_pk_add_f32 v[158:159], v[46:47], v[112:113]
	v_pk_mul_f32 v[114:115], v[48:49], v[114:115]
	v_pk_fma_f32 v[82:83], v[82:83], s[66:67], v[114:115] op_sel_hi:[1,0,1]
	v_pk_mul_f32 v[82:83], v[82:83], v[156:157]
	v_add_u32_e32 v6, 0x6000, v5
	global_store_dwordx2 v6, v[82:83], s[80:81]
	v_pk_mul_f32 v[116:117], v[48:49], v[116:117]
	v_pk_fma_f32 v[84:85], v[84:85], s[66:67], v[116:117] op_sel_hi:[1,0,1]
	v_pk_mul_f32 v[84:85], v[84:85], v[158:159]
	v_add_u32_e32 v6, 0xe000, v5
	global_store_dwordx2 v6, v[84:85], s[80:81]
	s_waitcnt lgkmcnt(0)
; HD float2 cmul(float2 a, float2 b){ return make_float2(a.x*b.x - a.y*b.y, a.x*b.y + a.y*b.x); }
; HD float2 cmulc(float2 a, float2 b){ return make_float2(a.x*b.x + a.y*b.y, a.y*b.x - a.x*b.y); }
; HD void inv12_half(const float2* Z, const float2* twA, const float2* twB, int t, float2& x0, float2& x1){
;   float2 w1=cmul(twA[t>>6],twB[t&63]), w2=cmul(w1,w1), w3=cmul(w2,w1);
;   float2 b0=Z[t], b1=cmulc(Z[t+4096],w1), b2=cmulc(Z[t+8192],w2), b3=cmulc(Z[t+12288],w3);
;   float2 s02=make_float2(b0.x+b2.x,b0.y+b2.y), d02=make_float2(b0.x-b2.x,b0.y-b2.y);
;   float2 s13=make_float2(b1.x+b3.x,b1.y+b3.y), d13=make_float2(b1.x-b3.x,b1.y-b3.y);
;   x0=make_float2(s02.x+s13.x,s02.y+s13.y);
;   x1=make_float2(d02.x-d13.y,d02.y+d13.x);
; }
; __device__ __forceinline__ void phase_hyena(KP kp_, int hf){ asm volatile("" : "+s"(kp_)); const Params p=load_params(kp_);
;     ...
;         if (st==1){ int tq=tid; asm volatile("" : "+v"(tq));
;           _Pragma("unroll 4") for (int i=0;i<8;++i){ int tb=tq+512*i; float2 xr[2]; inv12_half(Z,twA,twB,tb,xr[0],xr[1]);
;             _Pragma("unroll") for (int hh=0;hh<2;++hh){ int t=tb+hh*4096;
;               float u0=hconv3(rv,t,wv0,wv1,wv2,bv_), u1=hconv3(rv+8192,t,wv0,wv1,wv2,bv_);
;               float x0=hconv3(r1,t,wa0,wa1,wa2,ba_), x1=hconv3(r1+8192,t,wa0,wa1,wa2,ba_);
;               float2 y=xr[hh]; y.x*=(1.f/16384.f); y.y*=(1.f/16384.f);
;               Zs[t]=make_float2(x0*(y.x+u0*bias0), x1*(y.y+u1*bias0)); } }
	v_pk_mul_f32 v[222:223], v[58:59], v[10:11] op_sel:[1,1] op_sel_hi:[1,0]
	v_pk_fma_f32 v[22:23], v[58:59], v[10:11], v[222:223] op_sel:[0,0,0] op_sel_hi:[0,1,1] neg_lo:[0,0,1]
	v_pk_mul_f32 v[222:223], v[22:23], v[22:23] op_sel:[1,1] op_sel_hi:[1,0]
	v_pk_fma_f32 v[24:25], v[22:23], v[22:23], v[222:223] op_sel:[0,0,0] op_sel_hi:[0,1,1] neg_lo:[0,0,1]
	v_pk_mul_f32 v[222:223], v[24:25], v[22:23] op_sel:[1,1] op_sel_hi:[1,0]
	v_pk_fma_f32 v[26:27], v[24:25], v[22:23], v[222:223] op_sel:[0,0,0] op_sel_hi:[0,1,1] neg_lo:[0,0,1]
	v_pk_mul_f32 v[222:223], v[62:63], v[22:23] op_sel:[1,1] op_sel_hi:[0,1]
	v_pk_fma_f32 v[28:29], v[62:63], v[22:23], v[222:223] op_sel:[0,0,0] op_sel_hi:[1,0,1] neg_hi:[0,0,1]
	v_pk_mul_f32 v[222:223], v[64:65], v[24:25] op_sel:[1,1] op_sel_hi:[0,1]
	v_pk_fma_f32 v[30:31], v[64:65], v[24:25], v[222:223] op_sel:[0,0,0] op_sel_hi:[1,0,1] neg_hi:[0,0,1]
	v_pk_mul_f32 v[222:223], v[66:67], v[26:27] op_sel:[1,1] op_sel_hi:[0,1]
	v_pk_fma_f32 v[68:69], v[66:67], v[26:27], v[222:223] op_sel:[0,0,0] op_sel_hi:[1,0,1] neg_hi:[0,0,1]
	v_pk_add_f32 v[70:71], v[60:61], v[30:31]
	v_pk_add_f32 v[72:73], v[60:61], v[30:31] neg_lo:[0,1] neg_hi:[0,1]
	v_pk_add_f32 v[74:75], v[28:29], v[68:69]
	v_pk_add_f32 v[80:81], v[28:29], v[68:69] neg_lo:[0,1] neg_hi:[0,1]
	v_pk_add_f32 v[82:83], v[70:71], v[74:75]
	v_pk_add_f32 v[84:85], v[72:73], v[80:81] op_sel:[0,1] op_sel_hi:[1,0] neg_lo:[0,1]
	s_waitcnt vmcnt(2)
	v_lshlrev_b32_e32 v224, 16, v240
	v_lshlrev_b32_e32 v225, 16, v241
	v_mov_b32_e32 v226, 0
	v_mov_b32_e32 v227, 0
	v_mov_b32_e32 v110, 0
	v_mov_b32_e32 v111, 0
	v_mov_b32_dpp v226, v224 wave_shr:1 row_mask:0xf bank_mask:0xf
	v_mov_b32_dpp v227, v225 wave_shr:1 row_mask:0xf bank_mask:0xf
	v_mov_b32_dpp v110, v224 wave_shl:1 row_mask:0xf bank_mask:0xf
	v_mov_b32_dpp v111, v225 wave_shl:1 row_mask:0xf bank_mask:0xf
	v_pk_mul_f32 v[112:113], v[34:35], v[224:225]
	v_pk_fma_f32 v[112:113], v[32:33], v[226:227], v[112:113]
	v_pk_fma_f32 v[112:113], v[36:37], v[110:111], v[112:113]
	v_pk_add_f32 v[114:115], v[38:39], v[112:113]
	v_lshlrev_b32_e32 v224, 16, v242
	v_lshlrev_b32_e32 v225, 16, v243
	v_mov_b32_e32 v226, 0
	v_mov_b32_e32 v227, 0
	v_mov_b32_e32 v110, 0
	v_mov_b32_e32 v111, 0
	v_mov_b32_dpp v226, v224 wave_shr:1 row_mask:0xf bank_mask:0xf
	v_mov_b32_dpp v227, v225 wave_shr:1 row_mask:0xf bank_mask:0xf
	v_mov_b32_dpp v110, v224 wave_shl:1 row_mask:0xf bank_mask:0xf
	v_mov_b32_dpp v111, v225 wave_shl:1 row_mask:0xf bank_mask:0xf
	v_pk_mul_f32 v[112:113], v[42:43], v[224:225]
	v_pk_fma_f32 v[112:113], v[40:41], v[226:227], v[112:113]
	v_pk_fma_f32 v[112:113], v[44:45], v[110:111], v[112:113]
	v_pk_add_f32 v[156:157], v[46:47], v[112:113]
	v_lshlrev_b32_e32 v224, 16, v244
	v_lshlrev_b32_e32 v225, 16, v245
	v_mov_b32_e32 v226, 0
	v_mov_b32_e32 v227, 0
	v_mov_b32_e32 v110, 0
	v_mov_b32_e32 v111, 0
	v_mov_b32_dpp v226, v224 wave_shr:1 row_mask:0xf bank_mask:0xf
	v_mov_b32_dpp v227, v225 wave_shr:1 row_mask:0xf bank_mask:0xf
	v_mov_b32_dpp v110, v224 wave_shl:1 row_mask:0xf bank_mask:0xf
	v_mov_b32_dpp v111, v225 wave_shl:1 row_mask:0xf bank_mask:0xf
	v_pk_mul_f32 v[112:113], v[34:35], v[224:225]
	v_pk_fma_f32 v[112:113], v[32:33], v[226:227], v[112:113]
	v_pk_fma_f32 v[112:113], v[36:37], v[110:111], v[112:113]
	v_pk_add_f32 v[116:117], v[38:39], v[112:113]
	v_lshlrev_b32_e32 v224, 16, v246
	v_lshlrev_b32_e32 v225, 16, v247
	v_mov_b32_e32 v226, 0
	v_mov_b32_e32 v227, 0
	v_mov_b32_e32 v110, 0
	v_mov_b32_e32 v111, 0
	v_mov_b32_dpp v226, v224 wave_shr:1 row_mask:0xf bank_mask:0xf
	v_mov_b32_dpp v227, v225 wave_shr:1 row_mask:0xf bank_mask:0xf
	v_mov_b32_dpp v110, v224 wave_shl:1 row_mask:0xf bank_mask:0xf
	v_mov_b32_dpp v111, v225 wave_shl:1 row_mask:0xf bank_mask:0xf
	v_pk_mul_f32 v[112:113], v[42:43], v[224:225]
	v_pk_fma_f32 v[112:113], v[40:41], v[226:227], v[112:113]
	v_pk_fma_f32 v[112:113], v[44:45], v[110:111], v[112:113]
	v_pk_add_f32 v[158:159], v[46:47], v[112:113]
	v_pk_mul_f32 v[114:115], v[48:49], v[114:115]
	v_pk_fma_f32 v[82:83], v[82:83], s[66:67], v[114:115] op_sel_hi:[1,0,1]
	v_pk_mul_f32 v[82:83], v[82:83], v[156:157]
	v_add_u32_e32 v6, 0x7000, v5
	global_store_dwordx2 v6, v[82:83], s[80:81]
	v_pk_mul_f32 v[116:117], v[48:49], v[116:117]
	v_pk_fma_f32 v[84:85], v[84:85], s[66:67], v[116:117] op_sel_hi:[1,0,1]
	v_pk_mul_f32 v[84:85], v[84:85], v[158:159]
	v_add_u32_e32 v6, 0xf000, v5
	global_store_dwordx2 v6, v[84:85], s[80:81]
	s_mov_b32 s12, 0x8000
